# v31: conformer conv tap loop computes 8 output rows per pass (4 passes of 38 LDS row reads instead of 8 passes of 34: -44% LDS read traffic), FMA order per row unchanged
# baseline (speedup 1.0000x reference)
; #define LDS_WAIT() asm volatile("s_waitcnt lgkmcnt(0)" ::: "memory")
; __device__ __forceinline__ void conv_unit_p(const bf16* __restrict__ Z, bf16* __restrict__ CAT, float* __restrict__ newc, ...
;     ...
;     for (int tq = 0; tq < 32; tq += 4) {
;         float acc[4] = {bias, bias, bias, bias};
; #pragma unroll
;         for (int r = 0; r < 34; ++r) { const float gvv = gL[(tq + r) * 64 + lane];
; #pragma unroll
;             for (int q = 0; q < 4; ++q) { const int k = r - q; if (k >= 0 && k <= 30) acc[q] += wk[k] * gvv; } }
;         LDS_WAIT();
; #pragma unroll
;         for (int q = 0; q < 4; ++q) gL[(tq + q) * 64 + lane] = acc[q];
;     }
.LBB0_409:
	s_or_b64 exec, exec, s[6:7]
	s_waitcnt lgkmcnt(0)
	s_nop 0
	v_lshl_add_u32 v0, v124, 2, s69
	s_mov_b32 s2, -8
.LBB0_410:
	ds_read2st64_b32 v[136:137], v0 offset1:1
	ds_read2st64_b32 v[138:139], v0 offset0:2 offset1:3
	ds_read2st64_b32 v[140:141], v0 offset0:4 offset1:5
	ds_read2st64_b32 v[142:143], v0 offset0:6 offset1:7
	ds_read2st64_b32 v[144:145], v0 offset0:8 offset1:9
	ds_read2st64_b32 v[146:147], v0 offset0:10 offset1:11
	ds_read2st64_b32 v[148:149], v0 offset0:12 offset1:13
	ds_read2st64_b32 v[150:151], v0 offset0:14 offset1:15
	ds_read2st64_b32 v[152:153], v0 offset0:16 offset1:17
	ds_read2st64_b32 v[154:155], v0 offset0:18 offset1:19
	ds_read2st64_b32 v[156:157], v0 offset0:20 offset1:21
	ds_read2st64_b32 v[158:159], v0 offset0:22 offset1:23
	s_add_i32 s2, s2, 8
	v_add_u32_e32 v4, 0x800, v0
	s_waitcnt lgkmcnt(11)
	v_fma_f32 v1, v87, v136, v118
	v_fmac_f32_e32 v1, v88, v137
	v_fma_f32 v2, v87, v137, v118
	ds_read2st64_b32 v[160:161], v0 offset0:24 offset1:25
	s_waitcnt lgkmcnt(11)
	v_fmac_f32_e32 v1, v89, v138
	v_fmac_f32_e32 v2, v88, v138
	v_fma_f32 v3, v87, v138, v118
	v_fmac_f32_e32 v1, v90, v139
	v_fmac_f32_e32 v2, v89, v139
	v_fmac_f32_e32 v3, v88, v139
	v_fma_f32 v5, v87, v139, v118
	ds_read2st64_b32 v[162:163], v0 offset0:26 offset1:27
	s_waitcnt lgkmcnt(11)
	v_fmac_f32_e32 v1, v95, v140
	v_fmac_f32_e32 v2, v90, v140
	v_fmac_f32_e32 v3, v89, v140
	v_fmac_f32_e32 v5, v88, v140
	v_fma_f32 v194, v87, v140, v118
	v_fmac_f32_e32 v1, v91, v141
	v_fmac_f32_e32 v2, v95, v141
	v_fmac_f32_e32 v3, v90, v141
	v_fmac_f32_e32 v5, v89, v141
	v_fmac_f32_e32 v194, v88, v141
	v_fma_f32 v195, v87, v141, v118
	ds_read2st64_b32 v[164:165], v0 offset0:28 offset1:29
	s_waitcnt lgkmcnt(11)
	v_fmac_f32_e32 v1, v92, v142
	v_fmac_f32_e32 v2, v91, v142
	v_fmac_f32_e32 v3, v95, v142
	v_fmac_f32_e32 v5, v90, v142
	v_fmac_f32_e32 v194, v89, v142
	v_fmac_f32_e32 v195, v88, v142
	v_fma_f32 v196, v87, v142, v118
	v_fmac_f32_e32 v1, v93, v143
	v_fmac_f32_e32 v2, v92, v143
	v_fmac_f32_e32 v3, v91, v143
	v_fmac_f32_e32 v5, v95, v143
	v_fmac_f32_e32 v194, v90, v143
	v_fmac_f32_e32 v195, v89, v143
	v_fmac_f32_e32 v196, v88, v143
	v_fma_f32 v197, v87, v143, v118
	ds_read2st64_b32 v[166:167], v0 offset0:30 offset1:31
	s_waitcnt lgkmcnt(11)
	v_fmac_f32_e32 v1, v96, v144
	v_fmac_f32_e32 v2, v93, v144
	v_fmac_f32_e32 v3, v92, v144
	v_fmac_f32_e32 v5, v91, v144
	v_fmac_f32_e32 v194, v95, v144
	v_fmac_f32_e32 v195, v90, v144
	v_fmac_f32_e32 v196, v89, v144
	v_fmac_f32_e32 v197, v88, v144
	v_fmac_f32_e32 v1, v97, v145
	v_fmac_f32_e32 v2, v96, v145
	v_fmac_f32_e32 v3, v93, v145
	v_fmac_f32_e32 v5, v92, v145
	v_fmac_f32_e32 v194, v91, v145
	v_fmac_f32_e32 v195, v95, v145
	v_fmac_f32_e32 v196, v90, v145
	v_fmac_f32_e32 v197, v89, v145
	ds_read2st64_b32 v[188:189], v0 offset0:32 offset1:33
	s_waitcnt lgkmcnt(11)
	v_fmac_f32_e32 v1, v98, v146
	v_fmac_f32_e32 v2, v97, v146
	v_fmac_f32_e32 v3, v96, v146
	v_fmac_f32_e32 v5, v93, v146
	v_fmac_f32_e32 v194, v92, v146
	v_fmac_f32_e32 v195, v91, v146
	v_fmac_f32_e32 v196, v95, v146
	v_fmac_f32_e32 v197, v90, v146
	v_fmac_f32_e32 v1, v99, v147
	v_fmac_f32_e32 v2, v98, v147
	v_fmac_f32_e32 v3, v97, v147
	v_fmac_f32_e32 v5, v96, v147
	v_fmac_f32_e32 v194, v93, v147
	v_fmac_f32_e32 v195, v92, v147
	v_fmac_f32_e32 v196, v91, v147
	v_fmac_f32_e32 v197, v95, v147
	ds_read2st64_b32 v[190:191], v0 offset0:34 offset1:35
	s_waitcnt lgkmcnt(11)
	v_fmac_f32_e32 v1, v100, v148
	v_fmac_f32_e32 v2, v99, v148
	v_fmac_f32_e32 v3, v98, v148
	v_fmac_f32_e32 v5, v97, v148
	v_fmac_f32_e32 v194, v96, v148
	v_fmac_f32_e32 v195, v93, v148
	v_fmac_f32_e32 v196, v92, v148
	v_fmac_f32_e32 v197, v91, v148
	v_fmac_f32_e32 v1, v94, v149
	v_fmac_f32_e32 v2, v100, v149
	v_fmac_f32_e32 v3, v99, v149
	v_fmac_f32_e32 v5, v98, v149
	v_fmac_f32_e32 v194, v97, v149
	v_fmac_f32_e32 v195, v96, v149
	v_fmac_f32_e32 v196, v93, v149
	v_fmac_f32_e32 v197, v92, v149
	ds_read2st64_b32 v[192:193], v0 offset0:36 offset1:37
	s_waitcnt lgkmcnt(11)
	v_fmac_f32_e32 v1, v110, v150
	v_fmac_f32_e32 v2, v94, v150
	v_fmac_f32_e32 v3, v100, v150
	v_fmac_f32_e32 v5, v99, v150
	v_fmac_f32_e32 v194, v98, v150
	v_fmac_f32_e32 v195, v97, v150
	v_fmac_f32_e32 v196, v96, v150
	v_fmac_f32_e32 v197, v93, v150
	v_fmac_f32_e32 v1, v111, v151
	v_fmac_f32_e32 v2, v110, v151
	v_fmac_f32_e32 v3, v94, v151
	v_fmac_f32_e32 v5, v100, v151
	v_fmac_f32_e32 v194, v99, v151
	v_fmac_f32_e32 v195, v98, v151
	v_fmac_f32_e32 v196, v97, v151
	v_fmac_f32_e32 v197, v96, v151
	s_waitcnt lgkmcnt(10)
	v_fmac_f32_e32 v1, v101, v152
	v_fmac_f32_e32 v2, v111, v152
	v_fmac_f32_e32 v3, v110, v152
	v_fmac_f32_e32 v5, v94, v152
	v_fmac_f32_e32 v194, v100, v152
	v_fmac_f32_e32 v195, v99, v152
	v_fmac_f32_e32 v196, v98, v152
	v_fmac_f32_e32 v197, v97, v152
	v_fmac_f32_e32 v1, v102, v153
	v_fmac_f32_e32 v2, v101, v153
	v_fmac_f32_e32 v3, v111, v153
	v_fmac_f32_e32 v5, v110, v153
	v_fmac_f32_e32 v194, v94, v153
	v_fmac_f32_e32 v195, v100, v153
	v_fmac_f32_e32 v196, v99, v153
	v_fmac_f32_e32 v197, v98, v153
	s_waitcnt lgkmcnt(9)
	v_fmac_f32_e32 v1, v103, v154
	v_fmac_f32_e32 v2, v102, v154
	v_fmac_f32_e32 v3, v101, v154
	v_fmac_f32_e32 v5, v111, v154
	v_fmac_f32_e32 v194, v110, v154
	v_fmac_f32_e32 v195, v94, v154
	v_fmac_f32_e32 v196, v100, v154
	v_fmac_f32_e32 v197, v99, v154
	v_fmac_f32_e32 v1, v104, v155
	v_fmac_f32_e32 v2, v103, v155
	v_fmac_f32_e32 v3, v102, v155
	v_fmac_f32_e32 v5, v101, v155
	v_fmac_f32_e32 v194, v111, v155
	v_fmac_f32_e32 v195, v110, v155
	v_fmac_f32_e32 v196, v94, v155
	v_fmac_f32_e32 v197, v100, v155
	s_waitcnt lgkmcnt(8)
; #define LAS __attribute__((address_space(3)))
; #define LDS_WAIT() asm volatile("s_waitcnt lgkmcnt(0)" ::: "memory")
; __device__ __forceinline__ void conv_unit_p(const bf16* __restrict__ Z, bf16* __restrict__ CAT, float* __restrict__ newc, ...
;     ...
;     for (int tq = 0; tq < 32; tq += 4) {
;         float acc[4] = {bias, bias, bias, bias};
; #pragma unroll
;         for (int r = 0; r < 34; ++r) { const float gvv = gL[(tq + r) * 64 + lane];
; #pragma unroll
;             for (int q = 0; q < 4; ++q) { const int k = r - q; if (k >= 0 && k <= 30) acc[q] += wk[k] * gvv; } }
;         LDS_WAIT();
; #pragma unroll
;         for (int q = 0; q < 4; ++q) gL[(tq + q) * 64 + lane] = acc[q];
;     }
;     LDS_WAIT();
;     float gg[8], bb[8];
; #pragma unroll
;     for (int i = 0; i < 8; ++i) { gg[i] = lg[c0 + i]; bb[i] = lb[c0 + i]; }
;     bf16* ob = CAT + (rowbase + t0) * DP + 256 + c0;
; #pragma unroll
;     for (int j = 0; j < 4; ++j) { const int r = 8 * j + rr; const f32x4 a = *(const LAS f32x4*)(gL + r * 64 + cg * 8), b = *(const LAS f32x4*)(gL + r * 64 + cg * 8 + 4);
	v_fmac_f32_e32 v1, v105, v156
	v_fmac_f32_e32 v2, v104, v156
	v_fmac_f32_e32 v3, v103, v156
	v_fmac_f32_e32 v5, v102, v156
	v_fmac_f32_e32 v194, v101, v156
	v_fmac_f32_e32 v195, v111, v156
	v_fmac_f32_e32 v196, v110, v156
	v_fmac_f32_e32 v197, v94, v156
	v_fmac_f32_e32 v1, v112, v157
	v_fmac_f32_e32 v2, v105, v157
	v_fmac_f32_e32 v3, v104, v157
	v_fmac_f32_e32 v5, v103, v157
	v_fmac_f32_e32 v194, v102, v157
	v_fmac_f32_e32 v195, v101, v157
	v_fmac_f32_e32 v196, v111, v157
	v_fmac_f32_e32 v197, v110, v157
	s_waitcnt lgkmcnt(7)
	v_fmac_f32_e32 v1, v113, v158
	v_fmac_f32_e32 v2, v112, v158
	v_fmac_f32_e32 v3, v105, v158
	v_fmac_f32_e32 v5, v104, v158
	v_fmac_f32_e32 v194, v103, v158
	v_fmac_f32_e32 v195, v102, v158
	v_fmac_f32_e32 v196, v101, v158
	v_fmac_f32_e32 v197, v111, v158
	v_fmac_f32_e32 v1, v114, v159
	v_fmac_f32_e32 v2, v113, v159
	v_fmac_f32_e32 v3, v112, v159
	v_fmac_f32_e32 v5, v105, v159
	v_fmac_f32_e32 v194, v104, v159
	v_fmac_f32_e32 v195, v103, v159
	v_fmac_f32_e32 v196, v102, v159
	v_fmac_f32_e32 v197, v101, v159
	s_waitcnt lgkmcnt(6)
	v_fmac_f32_e32 v1, v106, v160
	v_fmac_f32_e32 v2, v114, v160
	v_fmac_f32_e32 v3, v113, v160
	v_fmac_f32_e32 v5, v112, v160
	v_fmac_f32_e32 v194, v105, v160
	v_fmac_f32_e32 v195, v104, v160
	v_fmac_f32_e32 v196, v103, v160
	v_fmac_f32_e32 v197, v102, v160
	v_fmac_f32_e32 v1, v107, v161
	v_fmac_f32_e32 v2, v106, v161
	v_fmac_f32_e32 v3, v114, v161
	v_fmac_f32_e32 v5, v113, v161
	v_fmac_f32_e32 v194, v112, v161
	v_fmac_f32_e32 v195, v105, v161
	v_fmac_f32_e32 v196, v104, v161
	v_fmac_f32_e32 v197, v103, v161
	s_waitcnt lgkmcnt(5)
	v_fmac_f32_e32 v1, v108, v162
	v_fmac_f32_e32 v2, v107, v162
	v_fmac_f32_e32 v3, v106, v162
	v_fmac_f32_e32 v5, v114, v162
	v_fmac_f32_e32 v194, v113, v162
	v_fmac_f32_e32 v195, v112, v162
	v_fmac_f32_e32 v196, v105, v162
	v_fmac_f32_e32 v197, v104, v162
	v_fmac_f32_e32 v1, v109, v163
	v_fmac_f32_e32 v2, v108, v163
	v_fmac_f32_e32 v3, v107, v163
	v_fmac_f32_e32 v5, v106, v163
	v_fmac_f32_e32 v194, v114, v163
	v_fmac_f32_e32 v195, v113, v163
	v_fmac_f32_e32 v196, v112, v163
	v_fmac_f32_e32 v197, v105, v163
	s_waitcnt lgkmcnt(4)
	v_fmac_f32_e32 v1, v115, v164
	v_fmac_f32_e32 v2, v109, v164
	v_fmac_f32_e32 v3, v108, v164
	v_fmac_f32_e32 v5, v107, v164
	v_fmac_f32_e32 v194, v106, v164
	v_fmac_f32_e32 v195, v114, v164
	v_fmac_f32_e32 v196, v113, v164
	v_fmac_f32_e32 v197, v112, v164
	v_fmac_f32_e32 v1, v116, v165
	v_fmac_f32_e32 v2, v115, v165
	v_fmac_f32_e32 v3, v109, v165
	v_fmac_f32_e32 v5, v108, v165
	v_fmac_f32_e32 v194, v107, v165
	v_fmac_f32_e32 v195, v106, v165
	v_fmac_f32_e32 v196, v114, v165
	v_fmac_f32_e32 v197, v113, v165
	s_waitcnt lgkmcnt(3)
	v_fmac_f32_e32 v1, v117, v166
	v_fmac_f32_e32 v2, v116, v166
	v_fmac_f32_e32 v3, v115, v166
	v_fmac_f32_e32 v5, v109, v166
	v_fmac_f32_e32 v194, v108, v166
	v_fmac_f32_e32 v195, v107, v166
	v_fmac_f32_e32 v196, v106, v166
	v_fmac_f32_e32 v197, v114, v166
	v_fmac_f32_e32 v2, v117, v167
	v_fmac_f32_e32 v3, v116, v167
	v_fmac_f32_e32 v5, v115, v167
	v_fmac_f32_e32 v194, v109, v167
	v_fmac_f32_e32 v195, v108, v167
	v_fmac_f32_e32 v196, v107, v167
	v_fmac_f32_e32 v197, v106, v167
	s_waitcnt lgkmcnt(2)
	v_fmac_f32_e32 v3, v117, v188
	v_fmac_f32_e32 v5, v116, v188
	v_fmac_f32_e32 v194, v115, v188
	v_fmac_f32_e32 v195, v109, v188
	v_fmac_f32_e32 v196, v108, v188
	v_fmac_f32_e32 v197, v107, v188
	v_fmac_f32_e32 v5, v117, v189
	v_fmac_f32_e32 v194, v116, v189
	v_fmac_f32_e32 v195, v115, v189
	v_fmac_f32_e32 v196, v109, v189
	v_fmac_f32_e32 v197, v108, v189
	s_waitcnt lgkmcnt(1)
	v_fmac_f32_e32 v194, v117, v190
	v_fmac_f32_e32 v195, v116, v190
	v_fmac_f32_e32 v196, v115, v190
	v_fmac_f32_e32 v197, v109, v190
	v_fmac_f32_e32 v195, v117, v191
	v_fmac_f32_e32 v196, v116, v191
	v_fmac_f32_e32 v197, v115, v191
	s_waitcnt lgkmcnt(0)
	v_fmac_f32_e32 v196, v117, v192
	v_fmac_f32_e32 v197, v116, v192
	v_fmac_f32_e32 v197, v117, v193
	s_cmp_lt_u32 s2, 24
	s_waitcnt lgkmcnt(0)
	ds_write2st64_b32 v0, v1, v2 offset1:1
	ds_write2st64_b32 v0, v3, v5 offset0:2 offset1:3
	ds_write2st64_b32 v0, v194, v195 offset0:4 offset1:5
	ds_write2st64_b32 v0, v196, v197 offset0:6 offset1:7
	v_mov_b32_e32 v0, v4
	s_cbranch_scc1 .LBB0_410
	v_mov_b64_e32 v[0:1], s[70:71]
	s_waitcnt lgkmcnt(0)
	v_mad_u64_u32 v[16:17], s[6:7], s84, v181, v[0:1]
	global_load_dwordx4 v[4:7], v128, s[54:55] offset:16
	global_load_dwordx4 v[12:15], v128, s[54:55]
	global_load_dwordx4 v[0:3], v128, s[26:27] offset:16
	global_load_dwordx4 v[8:11], v128, s[26:27]
	ds_read_b128 v[18:21], v67
	ds_read_b128 v[22:25], v67 offset:16
	s_or_b32 s4, s4, s74
	s_lshl_b64 s[4:5], s[4:5], 11
	v_lshl_add_u64 v[16:17], v[16:17], 0, s[4:5]
	s_waitcnt lgkmcnt(1)
	v_mov_b32_e32 v26, v18
	s_waitcnt lgkmcnt(0)
; #define LAS __attribute__((address_space(3)))
; __device__ __forceinline__ float sum8(float v) { v += dpp_get<0xB1, 0xF>(v); v += dpp_get<0x4E, 0xF>(v); v += dpp_get<0x141, 0xF>(v); return v; }
; __device__ __forceinline__ v4u pack8(const float (&f)[8]) { v4u w; w.x = pg8::cvt_pk_bf16(f[0], f[1]); w.y = pg8::cvt_pk_bf16(f[2], f[3]); w.z = pg8::cvt_pk_bf16(f[4], f[5]); w.w = pg8::cvt_pk_bf16(f[6], f[7]); return w; }
; __device__ __forceinline__ float sigm(float x) { return __builtin_amdgcn_rcpf(1.f + __builtin_amdgcn_exp2f(-1.44269504f * x)); }
; __device__ __forceinline__ void conv_unit_p(const bf16* __restrict__ Z, bf16* __restrict__ CAT, float* __restrict__ newc, ...
;     ...
;     float gg[8], bb[8];
; #pragma unroll
;     for (int i = 0; i < 8; ++i) { gg[i] = lg[c0 + i]; bb[i] = lb[c0 + i]; }
;     bf16* ob = CAT + (rowbase + t0) * DP + 256 + c0;
; #pragma unroll
;     for (int j = 0; j < 4; ++j) { const int r = 8 * j + rr; const f32x4 a = *(const LAS f32x4*)(gL + r * 64 + cg * 8), b = *(const LAS f32x4*)(gL + r * 64 + cg * 8 + 4);
;         float x[8] = {a[0], a[1], a[2], a[3], b[0], b[1], b[2], b[3]};
;         const float mean = sum8(((x[0] + x[1]) + (x[2] + x[3])) + ((x[4] + x[5]) + (x[6] + x[7]))) * (1.f / 64.f);
;         float q = 0.f;
; #pragma unroll
;         for (int i = 0; i < 8; ++i) { x[i] -= mean; q += x[i] * x[i]; }
;         const float rstd = rsqrtf(sum8(q) * (1.f / 64.f) + EPS);
; #pragma unroll
;         for (int i = 0; i < 8; ++i) { const float yy = x[i] * rstd * gg[i] + bb[i]; x[i] = yy * sigm(yy); }
;         *(v4u*)(ob + r * DP) = pack8(x); }
	v_mov_b32_e32 v27, v22
	v_mov_b32_e32 v28, v19
	v_mov_b32_e32 v29, v23
	v_pk_add_f32 v[26:27], v[26:27], v[28:29]
	v_mov_b32_e32 v28, v20
	v_mov_b32_e32 v29, v24
	v_mov_b32_e32 v30, v21
	v_mov_b32_e32 v31, v25
	v_pk_add_f32 v[28:29], v[28:29], v[30:31]
	v_mov_b32_e32 v65, v129
	v_pk_add_f32 v[26:27], v[26:27], v[28:29]
	v_lshl_add_u64 v[16:17], v[16:17], 0, v[64:65]
	v_add_f32_e32 v26, v26, v27
	s_mov_b64 s[4:5], 0x900200
	v_lshl_add_u64 v[16:17], v[16:17], 0, s[4:5]
	v_add_f32_dpp v26, v26, v26 quad_perm:[1,0,3,2] row_mask:0xf bank_mask:0xf bound_ctrl:1
	s_mov_b32 s2, 36
	v_readlane_b32 s70, v254, 58
	v_add_f32_dpp v26, v26, v26 quad_perm:[2,3,0,1] row_mask:0xf bank_mask:0xf bound_ctrl:1
	s_nop 1
	v_add_f32_dpp v26, v26, v26 row_half_mirror row_mask:0xf bank_mask:0xf bound_ctrl:1
	v_mul_f32_e32 v26, 0x3c800000, v26
	v_pk_add_f32 v[28:29], v[18:19], v[26:27] op_sel_hi:[1,0] neg_lo:[0,1] neg_hi:[0,1]
	v_pk_add_f32 v[20:21], v[20:21], v[26:27] op_sel_hi:[1,0] neg_lo:[0,1] neg_hi:[0,1]
	v_pk_mul_f32 v[30:31], v[28:29], v[28:29]
	v_pk_mul_f32 v[32:33], v[20:21], v[20:21]
	v_pk_add_f32 v[22:23], v[22:23], v[26:27] op_sel_hi:[1,0] neg_lo:[0,1] neg_hi:[0,1]
	v_pk_add_f32 v[18:19], v[24:25], v[26:27] op_sel_hi:[1,0] neg_lo:[0,1] neg_hi:[0,1]
	v_add_f32_e32 v26, v30, v31
	v_add_f32_e32 v26, v32, v26
	v_pk_mul_f32 v[34:35], v[22:23], v[22:23]
	v_add_f32_e32 v26, v33, v26
	v_add_f32_e32 v26, v34, v26
	v_pk_mul_f32 v[24:25], v[18:19], v[18:19]
	v_add_f32_e32 v26, v35, v26
	v_add_f32_e32 v24, v24, v26
	v_add_f32_e32 v24, v25, v24
	s_nop 1
	v_add_f32_dpp v24, v24, v24 quad_perm:[1,0,3,2] row_mask:0xf bank_mask:0xf bound_ctrl:1
	s_nop 1
	v_add_f32_dpp v24, v24, v24 quad_perm:[2,3,0,1] row_mask:0xf bank_mask:0xf bound_ctrl:1
	s_nop 1
	v_add_f32_dpp v24, v24, v24 row_half_mirror row_mask:0xf bank_mask:0xf bound_ctrl:1
	v_fmamk_f32 v24, v24, 0x3c800000, v168
	v_cmp_gt_f32_e32 vcc, s79, v24
	v_mul_f32_e32 v25, 0x4b800000, v24
	s_nop 0
	v_cndmask_b32_e32 v24, v24, v25, vcc
	v_rsq_f32_e32 v24, v24
	s_nop 0
	v_mul_f32_e32 v25, 0x45800000, v24
	v_cndmask_b32_e32 v24, v24, v25, vcc
	v_mul_f32_e32 v25, v28, v24
	v_mul_f32_e32 v20, v20, v24
	v_mul_f32_e32 v21, v21, v24
	v_mul_f32_e32 v22, v22, v24
	v_mul_f32_e32 v23, v23, v24
	v_mul_f32_e32 v18, v18, v24
	s_waitcnt vmcnt(1)
	v_fma_f32 v22, v4, v22, v0
	s_waitcnt vmcnt(0)
	v_fma_f32 v25, v12, v25, v8
	v_mul_f32_e32 v26, 0xbfb8aa3b, v25
	v_exp_f32_e32 v26, v26
	v_fma_f32 v20, v14, v20, v10
	v_fma_f32 v21, v15, v21, v11
	v_fma_f32 v23, v5, v23, v1
	v_add_f32_e32 v26, 1.0, v26
	v_rcp_f32_e32 v26, v26
	v_fma_f32 v18, v6, v18, v2
	v_mul_f32_e32 v25, v25, v26
	v_mul_f32_e32 v26, v29, v24
	v_fma_f32 v26, v13, v26, v9
	v_mul_f32_e32 v27, 0xbfb8aa3b, v26
	v_exp_f32_e32 v27, v27
	s_nop 0
	v_add_f32_e32 v27, 1.0, v27
	v_rcp_f32_e32 v27, v27
	s_nop 0
	v_mul_f32_e32 v26, v26, v27
	v_mul_f32_e32 v27, 0xbfb8aa3b, v20
	v_exp_f32_e32 v27, v27
	s_nop 0
	v_add_f32_e32 v27, 1.0, v27
	v_rcp_f32_e32 v27, v27
	s_nop 0
	v_mul_f32_e32 v20, v20, v27
	v_mul_f32_e32 v27, 0xbfb8aa3b, v21
	v_exp_f32_e32 v27, v27
	s_nop 0
	v_add_f32_e32 v27, 1.0, v27
	v_rcp_f32_e32 v27, v27
	s_nop 0
	v_mul_f32_e32 v21, v21, v27
	v_mul_f32_e32 v27, 0xbfb8aa3b, v22
	v_exp_f32_e32 v27, v27
	s_nop 0
	v_add_f32_e32 v27, 1.0, v27
	v_rcp_f32_e32 v27, v27
	s_nop 0
	v_mul_f32_e32 v22, v22, v27
	v_mul_f32_e32 v27, 0xbfb8aa3b, v23
	v_exp_f32_e32 v27, v27
	s_nop 0
	v_add_f32_e32 v27, 1.0, v27
	v_rcp_f32_e32 v27, v27
	s_nop 0
	v_mul_f32_e32 v23, v23, v27
	v_mul_f32_e32 v27, 0xbfb8aa3b, v18
	v_exp_f32_e32 v27, v27
	s_nop 0
	v_add_f32_e32 v27, 1.0, v27
	v_rcp_f32_e32 v27, v27
	s_nop 0
	v_mul_f32_e32 v27, v18, v27
	v_mul_f32_e32 v18, v19, v24
	v_fma_f32 v18, v7, v18, v3
	v_mul_f32_e32 v19, 0xbfb8aa3b, v18
	v_exp_f32_e32 v19, v19
	s_nop 0
	v_add_f32_e32 v19, 1.0, v19
	v_rcp_f32_e32 v19, v19
	s_nop 0
	v_mul_f32_e32 v24, v18, v19
	v_cvt_pk_bf16_f32 v18, v25, v26
	v_cvt_pk_bf16_f32 v19, v20, v21
	v_cvt_pk_bf16_f32 v20, v22, v23
	v_lshlrev_b32_e32 v22, 10, v86
	v_ashrrev_i32_e32 v23, 31, v22
	v_lshl_add_u64 v[22:23], v[22:23], 1, v[16:17]
	v_cvt_pk_bf16_f32 v21, v27, v24
	global_store_dwordx4 v[22:23], v[18:21], off
	ds_read_b128 v[18:21], v56
	ds_read_b128 v[22:25], v56 offset:16
	s_waitcnt lgkmcnt(1)
	v_mov_b32_e32 v26, v18
	s_waitcnt lgkmcnt(0)
; #define LAS __attribute__((address_space(3)))
; __device__ __forceinline__ float sum8(float v) { v += dpp_get<0xB1, 0xF>(v); v += dpp_get<0x4E, 0xF>(v); v += dpp_get<0x141, 0xF>(v); return v; }
; __device__ __forceinline__ v4u pack8(const float (&f)[8]) { v4u w; w.x = pg8::cvt_pk_bf16(f[0], f[1]); w.y = pg8::cvt_pk_bf16(f[2], f[3]); w.z = pg8::cvt_pk_bf16(f[4], f[5]); w.w = pg8::cvt_pk_bf16(f[6], f[7]); return w; }
; __device__ __forceinline__ float sigm(float x) { return __builtin_amdgcn_rcpf(1.f + __builtin_amdgcn_exp2f(-1.44269504f * x)); }
; __device__ __forceinline__ void conv_unit_p(const bf16* __restrict__ Z, bf16* __restrict__ CAT, float* __restrict__ newc, ...
;     ...
;     float gg[8], bb[8];
; #pragma unroll
;     for (int i = 0; i < 8; ++i) { gg[i] = lg[c0 + i]; bb[i] = lb[c0 + i]; }
;     bf16* ob = CAT + (rowbase + t0) * DP + 256 + c0;
; #pragma unroll
;     for (int j = 0; j < 4; ++j) { const int r = 8 * j + rr; const f32x4 a = *(const LAS f32x4*)(gL + r * 64 + cg * 8), b = *(const LAS f32x4*)(gL + r * 64 + cg * 8 + 4);
;         float x[8] = {a[0], a[1], a[2], a[3], b[0], b[1], b[2], b[3]};
;         const float mean = sum8(((x[0] + x[1]) + (x[2] + x[3])) + ((x[4] + x[5]) + (x[6] + x[7]))) * (1.f / 64.f);
;         float q = 0.f;
; #pragma unroll
;         for (int i = 0; i < 8; ++i) { x[i] -= mean; q += x[i] * x[i]; }
;         const float rstd = rsqrtf(sum8(q) * (1.f / 64.f) + EPS);
; #pragma unroll
;         for (int i = 0; i < 8; ++i) { const float yy = x[i] * rstd * gg[i] + bb[i]; x[i] = yy * sigm(yy); }
;         *(v4u*)(ob + r * DP) = pack8(x); }
	v_mov_b32_e32 v27, v22
	v_mov_b32_e32 v28, v19
	v_mov_b32_e32 v29, v23
	v_pk_add_f32 v[26:27], v[26:27], v[28:29]
	v_mov_b32_e32 v28, v20
	v_mov_b32_e32 v29, v24
	v_mov_b32_e32 v30, v21
	v_mov_b32_e32 v31, v25
	v_pk_add_f32 v[28:29], v[28:29], v[30:31]
	s_nop 0
	v_pk_add_f32 v[26:27], v[26:27], v[28:29]
	s_nop 0
	v_add_f32_e32 v26, v26, v27
	s_nop 1
	v_add_f32_dpp v26, v26, v26 quad_perm:[1,0,3,2] row_mask:0xf bank_mask:0xf bound_ctrl:1
	s_nop 1
	v_add_f32_dpp v26, v26, v26 quad_perm:[2,3,0,1] row_mask:0xf bank_mask:0xf bound_ctrl:1
	s_nop 1
	v_add_f32_dpp v26, v26, v26 row_half_mirror row_mask:0xf bank_mask:0xf bound_ctrl:1
	v_mul_f32_e32 v26, 0x3c800000, v26
	v_pk_add_f32 v[18:19], v[18:19], v[26:27] op_sel_hi:[1,0] neg_lo:[0,1] neg_hi:[0,1]
	v_pk_add_f32 v[20:21], v[20:21], v[26:27] op_sel_hi:[1,0] neg_lo:[0,1] neg_hi:[0,1]
	v_pk_mul_f32 v[28:29], v[18:19], v[18:19]
	v_pk_mul_f32 v[30:31], v[20:21], v[20:21]
	v_add_f32_e32 v28, v28, v29
	v_pk_add_f32 v[22:23], v[22:23], v[26:27] op_sel_hi:[1,0] neg_lo:[0,1] neg_hi:[0,1]
	v_add_f32_e32 v28, v30, v28
	v_pk_mul_f32 v[32:33], v[22:23], v[22:23]
	v_add_f32_e32 v28, v31, v28
	v_pk_add_f32 v[24:25], v[24:25], v[26:27] op_sel_hi:[1,0] neg_lo:[0,1] neg_hi:[0,1]
	v_add_f32_e32 v28, v32, v28
	v_pk_mul_f32 v[26:27], v[24:25], v[24:25]
	v_add_f32_e32 v28, v33, v28
	v_add_f32_e32 v26, v26, v28
	v_add_f32_e32 v26, v27, v26
	s_nop 1
	v_add_f32_dpp v26, v26, v26 quad_perm:[1,0,3,2] row_mask:0xf bank_mask:0xf bound_ctrl:1
	s_nop 1
	v_add_f32_dpp v26, v26, v26 quad_perm:[2,3,0,1] row_mask:0xf bank_mask:0xf bound_ctrl:1
	s_nop 1
	v_add_f32_dpp v26, v26, v26 row_half_mirror row_mask:0xf bank_mask:0xf bound_ctrl:1
	v_fmamk_f32 v26, v26, 0x3c800000, v168
	v_cmp_gt_f32_e32 vcc, s79, v26
	v_mul_f32_e32 v27, 0x4b800000, v26
	s_nop 0
	v_cndmask_b32_e32 v26, v26, v27, vcc
	v_rsq_f32_e32 v26, v26
	s_nop 0
	v_mul_f32_e32 v27, 0x45800000, v26
	v_cndmask_b32_e32 v26, v26, v27, vcc
	v_mul_f32_e32 v18, v18, v26
	v_fma_f32 v18, v12, v18, v8
	v_mul_f32_e32 v27, 0xbfb8aa3b, v18
	v_exp_f32_e32 v27, v27
	v_mul_f32_e32 v19, v19, v26
	v_fma_f32 v19, v13, v19, v9
	v_mul_f32_e32 v20, v20, v26
	v_add_f32_e32 v27, 1.0, v27
	v_rcp_f32_e32 v27, v27
	v_fma_f32 v20, v14, v20, v10
	v_mul_f32_e32 v21, v21, v26
	v_fma_f32 v21, v15, v21, v11
	v_mul_f32_e32 v18, v18, v27
	v_mul_f32_e32 v27, 0xbfb8aa3b, v19
	v_exp_f32_e32 v27, v27
	v_mul_f32_e32 v22, v22, v26
	v_fma_f32 v22, v4, v22, v0
	v_mul_f32_e32 v23, v23, v26
	v_add_f32_e32 v27, 1.0, v27
	v_rcp_f32_e32 v27, v27
	v_fma_f32 v23, v5, v23, v1
	v_mul_f32_e32 v24, v24, v26
	v_mul_f32_e32 v25, v25, v26
	v_mul_f32_e32 v19, v19, v27
	v_mul_f32_e32 v27, 0xbfb8aa3b, v20
	v_exp_f32_e32 v27, v27
	v_fma_f32 v24, v6, v24, v2
	v_fma_f32 v25, v7, v25, v3
	v_mul_f32_e32 v26, 0xbfb8aa3b, v25
	v_add_f32_e32 v27, 1.0, v27
	v_rcp_f32_e32 v27, v27
	v_exp_f32_e32 v26, v26
	v_cvt_pk_bf16_f32 v18, v18, v19
	v_mul_f32_e32 v20, v20, v27
	v_mul_f32_e32 v27, 0xbfb8aa3b, v21
	v_exp_f32_e32 v27, v27
	v_add_f32_e32 v26, 1.0, v26
	v_rcp_f32_e32 v26, v26
	v_add_f32_e32 v27, 1.0, v27
	v_rcp_f32_e32 v27, v27
	v_mul_f32_e32 v25, v25, v26
	v_mul_f32_e32 v21, v21, v27
	v_mul_f32_e32 v27, 0xbfb8aa3b, v22
	v_exp_f32_e32 v27, v27
	v_cvt_pk_bf16_f32 v19, v20, v21
	s_nop 0
	v_add_f32_e32 v27, 1.0, v27
	v_rcp_f32_e32 v27, v27
	s_nop 0
	v_mul_f32_e32 v22, v22, v27
	v_mul_f32_e32 v27, 0xbfb8aa3b, v23
	v_exp_f32_e32 v27, v27
	s_nop 0
	v_add_f32_e32 v27, 1.0, v27
	v_rcp_f32_e32 v27, v27
	s_nop 0
	v_mul_f32_e32 v23, v23, v27
	v_mul_f32_e32 v27, 0xbfb8aa3b, v24
	v_exp_f32_e32 v27, v27
	v_cvt_pk_bf16_f32 v20, v22, v23
	v_lshlrev_b32_e32 v22, 10, v85
	v_ashrrev_i32_e32 v23, 31, v22
	v_add_f32_e32 v27, 1.0, v27
	v_rcp_f32_e32 v27, v27
	v_lshl_add_u64 v[22:23], v[22:23], 1, v[16:17]
	v_mul_f32_e32 v24, v24, v27
	v_cvt_pk_bf16_f32 v21, v24, v25
	global_store_dwordx4 v[22:23], v[18:21], off
	ds_read_b128 v[18:21], v48
	ds_read_b128 v[22:25], v48 offset:16
	s_waitcnt lgkmcnt(1)
	v_mov_b32_e32 v26, v18
	s_waitcnt lgkmcnt(0)
	v_mov_b32_e32 v27, v22
	v_mov_b32_e32 v28, v19
	v_mov_b32_e32 v29, v23
	v_pk_add_f32 v[26:27], v[26:27], v[28:29]
	v_mov_b32_e32 v28, v20
	v_mov_b32_e32 v29, v24
	v_mov_b32_e32 v30, v21
	v_mov_b32_e32 v31, v25
	v_pk_add_f32 v[28:29], v[28:29], v[30:31]
	s_nop 0
	v_pk_add_f32 v[26:27], v[26:27], v[28:29]
	s_nop 0
	v_add_f32_e32 v26, v26, v27
	s_nop 1
	v_add_f32_dpp v26, v26, v26 quad_perm:[1,0,3,2] row_mask:0xf bank_mask:0xf bound_ctrl:1
	s_nop 1
	v_add_f32_dpp v26, v26, v26 quad_perm:[2,3,0,1] row_mask:0xf bank_mask:0xf bound_ctrl:1
	s_nop 1
	v_add_f32_dpp v26, v26, v26 row_half_mirror row_mask:0xf bank_mask:0xf bound_ctrl:1
	v_mul_f32_e32 v26, 0x3c800000, v26
	v_pk_add_f32 v[18:19], v[18:19], v[26:27] op_sel_hi:[1,0] neg_lo:[0,1] neg_hi:[0,1]
	v_pk_add_f32 v[20:21], v[20:21], v[26:27] op_sel_hi:[1,0] neg_lo:[0,1] neg_hi:[0,1]
	v_pk_mul_f32 v[28:29], v[18:19], v[18:19]
	v_pk_mul_f32 v[30:31], v[20:21], v[20:21]
	v_add_f32_e32 v28, v28, v29
	v_pk_add_f32 v[22:23], v[22:23], v[26:27] op_sel_hi:[1,0] neg_lo:[0,1] neg_hi:[0,1]
	v_add_f32_e32 v28, v30, v28
	v_pk_mul_f32 v[32:33], v[22:23], v[22:23]
	v_add_f32_e32 v28, v31, v28
	v_pk_add_f32 v[24:25], v[24:25], v[26:27] op_sel_hi:[1,0] neg_lo:[0,1] neg_hi:[0,1]
	v_add_f32_e32 v28, v32, v28
	v_pk_mul_f32 v[26:27], v[24:25], v[24:25]
	v_add_f32_e32 v28, v33, v28
	v_add_f32_e32 v26, v26, v28
	v_add_f32_e32 v26, v27, v26
	s_nop 1
	v_add_f32_dpp v26, v26, v26 quad_perm:[1,0,3,2] row_mask:0xf bank_mask:0xf bound_ctrl:1
	s_nop 1
	v_add_f32_dpp v26, v26, v26 quad_perm:[2,3,0,1] row_mask:0xf bank_mask:0xf bound_ctrl:1
	s_nop 1
	v_add_f32_dpp v26, v26, v26 row_half_mirror row_mask:0xf bank_mask:0xf bound_ctrl:1
; #define LAS __attribute__((address_space(3)))
; __device__ __forceinline__ float sum8(float v) { v += dpp_get<0xB1, 0xF>(v); v += dpp_get<0x4E, 0xF>(v); v += dpp_get<0x141, 0xF>(v); return v; }
; __device__ __forceinline__ v4u pack8(const float (&f)[8]) { v4u w; w.x = pg8::cvt_pk_bf16(f[0], f[1]); w.y = pg8::cvt_pk_bf16(f[2], f[3]); w.z = pg8::cvt_pk_bf16(f[4], f[5]); w.w = pg8::cvt_pk_bf16(f[6], f[7]); return w; }
; __device__ __forceinline__ float sigm(float x) { return __builtin_amdgcn_rcpf(1.f + __builtin_amdgcn_exp2f(-1.44269504f * x)); }
; __device__ __forceinline__ void conv_unit_p(const bf16* __restrict__ Z, bf16* __restrict__ CAT, float* __restrict__ newc, ...
;     ...
;     float gg[8], bb[8];
; #pragma unroll
;     for (int i = 0; i < 8; ++i) { gg[i] = lg[c0 + i]; bb[i] = lb[c0 + i]; }
;     bf16* ob = CAT + (rowbase + t0) * DP + 256 + c0;
; #pragma unroll
;     for (int j = 0; j < 4; ++j) { const int r = 8 * j + rr; const f32x4 a = *(const LAS f32x4*)(gL + r * 64 + cg * 8), b = *(const LAS f32x4*)(gL + r * 64 + cg * 8 + 4);
;         float x[8] = {a[0], a[1], a[2], a[3], b[0], b[1], b[2], b[3]};
;         const float mean = sum8(((x[0] + x[1]) + (x[2] + x[3])) + ((x[4] + x[5]) + (x[6] + x[7]))) * (1.f / 64.f);
;         float q = 0.f;
; #pragma unroll
;         for (int i = 0; i < 8; ++i) { x[i] -= mean; q += x[i] * x[i]; }
;         const float rstd = rsqrtf(sum8(q) * (1.f / 64.f) + EPS);
; #pragma unroll
;         for (int i = 0; i < 8; ++i) { const float yy = x[i] * rstd * gg[i] + bb[i]; x[i] = yy * sigm(yy); }
;         *(v4u*)(ob + r * DP) = pack8(x); }
	v_fmamk_f32 v26, v26, 0x3c800000, v168
	v_cmp_gt_f32_e32 vcc, s79, v26
	v_mul_f32_e32 v27, 0x4b800000, v26
	s_nop 0
	v_cndmask_b32_e32 v26, v26, v27, vcc
	v_rsq_f32_e32 v26, v26
	s_nop 0
	v_mul_f32_e32 v27, 0x45800000, v26
	v_cndmask_b32_e32 v26, v26, v27, vcc
	v_mul_f32_e32 v18, v18, v26
	v_fma_f32 v18, v12, v18, v8
	v_mul_f32_e32 v27, 0xbfb8aa3b, v18
	v_exp_f32_e32 v27, v27
	v_mul_f32_e32 v19, v19, v26
	v_fma_f32 v19, v13, v19, v9
	v_mul_f32_e32 v20, v20, v26
	v_add_f32_e32 v27, 1.0, v27
	v_rcp_f32_e32 v27, v27
	v_fma_f32 v20, v14, v20, v10
	v_mul_f32_e32 v21, v21, v26
	v_fma_f32 v21, v15, v21, v11
	v_mul_f32_e32 v18, v18, v27
	v_mul_f32_e32 v27, 0xbfb8aa3b, v19
	v_exp_f32_e32 v27, v27
	v_mul_f32_e32 v22, v22, v26
	v_fma_f32 v22, v4, v22, v0
	v_mul_f32_e32 v23, v23, v26
	v_add_f32_e32 v27, 1.0, v27
	v_rcp_f32_e32 v27, v27
	v_fma_f32 v23, v5, v23, v1
	v_mul_f32_e32 v24, v24, v26
	v_mul_f32_e32 v25, v25, v26
	v_mul_f32_e32 v19, v19, v27
	v_mul_f32_e32 v27, 0xbfb8aa3b, v20
	v_exp_f32_e32 v27, v27
	v_fma_f32 v24, v6, v24, v2
	v_fma_f32 v25, v7, v25, v3
	v_mul_f32_e32 v26, 0xbfb8aa3b, v25
	v_add_f32_e32 v27, 1.0, v27
	v_rcp_f32_e32 v27, v27
	v_exp_f32_e32 v26, v26
	v_cvt_pk_bf16_f32 v18, v18, v19
	v_mul_f32_e32 v20, v20, v27
	v_mul_f32_e32 v27, 0xbfb8aa3b, v21
	v_exp_f32_e32 v27, v27
	v_add_f32_e32 v26, 1.0, v26
	v_rcp_f32_e32 v26, v26
	v_add_f32_e32 v27, 1.0, v27
	v_rcp_f32_e32 v27, v27
	v_mul_f32_e32 v25, v25, v26
	v_mul_f32_e32 v21, v21, v27
	v_mul_f32_e32 v27, 0xbfb8aa3b, v22
	v_exp_f32_e32 v27, v27
	v_cvt_pk_bf16_f32 v19, v20, v21
	s_nop 0
	v_add_f32_e32 v27, 1.0, v27
	v_rcp_f32_e32 v27, v27
	s_nop 0
	v_mul_f32_e32 v22, v22, v27
	v_mul_f32_e32 v27, 0xbfb8aa3b, v23
	v_exp_f32_e32 v27, v27
	s_nop 0
	v_add_f32_e32 v27, 1.0, v27
	v_rcp_f32_e32 v27, v27
	s_nop 0
	v_mul_f32_e32 v23, v23, v27
	v_mul_f32_e32 v27, 0xbfb8aa3b, v24
	v_exp_f32_e32 v27, v27
	v_cvt_pk_bf16_f32 v20, v22, v23
	v_lshlrev_b32_e32 v22, 10, v83
	v_ashrrev_i32_e32 v23, 31, v22
	v_add_f32_e32 v27, 1.0, v27
	v_rcp_f32_e32 v27, v27
	v_lshl_add_u64 v[22:23], v[22:23], 1, v[16:17]
	v_mul_f32_e32 v24, v24, v27
	v_cvt_pk_bf16_f32 v21, v24, v25
	global_store_dwordx4 v[22:23], v[18:21], off
	ds_read_b128 v[18:21], v40
	ds_read_b128 v[22:25], v40 offset:16
	s_waitcnt lgkmcnt(1)
	v_mov_b32_e32 v26, v18
	s_waitcnt lgkmcnt(0)
	v_mov_b32_e32 v27, v22
	v_mov_b32_e32 v28, v19
	v_mov_b32_e32 v29, v23
	v_pk_add_f32 v[26:27], v[26:27], v[28:29]
	v_mov_b32_e32 v28, v20
	v_mov_b32_e32 v29, v24
	v_mov_b32_e32 v30, v21
	v_mov_b32_e32 v31, v25
	v_pk_add_f32 v[28:29], v[28:29], v[30:31]
	s_nop 0
	v_pk_add_f32 v[26:27], v[26:27], v[28:29]
	s_nop 0
	v_add_f32_e32 v26, v26, v27
	s_nop 1
	v_add_f32_dpp v26, v26, v26 quad_perm:[1,0,3,2] row_mask:0xf bank_mask:0xf bound_ctrl:1
	s_nop 1
	v_add_f32_dpp v26, v26, v26 quad_perm:[2,3,0,1] row_mask:0xf bank_mask:0xf bound_ctrl:1
	s_nop 1
	v_add_f32_dpp v26, v26, v26 row_half_mirror row_mask:0xf bank_mask:0xf bound_ctrl:1
	v_mul_f32_e32 v26, 0x3c800000, v26
	v_pk_add_f32 v[18:19], v[18:19], v[26:27] op_sel_hi:[1,0] neg_lo:[0,1] neg_hi:[0,1]
	v_pk_add_f32 v[20:21], v[20:21], v[26:27] op_sel_hi:[1,0] neg_lo:[0,1] neg_hi:[0,1]
	v_pk_mul_f32 v[28:29], v[18:19], v[18:19]
	v_pk_mul_f32 v[30:31], v[20:21], v[20:21]
	v_add_f32_e32 v28, v28, v29
	v_pk_add_f32 v[22:23], v[22:23], v[26:27] op_sel_hi:[1,0] neg_lo:[0,1] neg_hi:[0,1]
	v_add_f32_e32 v28, v30, v28
	v_pk_mul_f32 v[32:33], v[22:23], v[22:23]
	v_add_f32_e32 v28, v31, v28
	v_pk_add_f32 v[24:25], v[24:25], v[26:27] op_sel_hi:[1,0] neg_lo:[0,1] neg_hi:[0,1]
	v_add_f32_e32 v28, v32, v28
	v_pk_mul_f32 v[26:27], v[24:25], v[24:25]
	v_add_f32_e32 v28, v33, v28
	v_add_f32_e32 v26, v26, v28
	v_add_f32_e32 v26, v27, v26
	s_nop 1
	v_add_f32_dpp v26, v26, v26 quad_perm:[1,0,3,2] row_mask:0xf bank_mask:0xf bound_ctrl:1
	s_nop 1
	v_add_f32_dpp v26, v26, v26 quad_perm:[2,3,0,1] row_mask:0xf bank_mask:0xf bound_ctrl:1
	s_nop 1
	v_add_f32_dpp v26, v26, v26 row_half_mirror row_mask:0xf bank_mask:0xf bound_ctrl:1
	v_fmamk_f32 v26, v26, 0x3c800000, v168
	v_cmp_gt_f32_e32 vcc, s79, v26
	v_mul_f32_e32 v27, 0x4b800000, v26
	s_nop 0
	v_cndmask_b32_e32 v26, v26, v27, vcc
	v_rsq_f32_e32 v26, v26
	s_nop 0
	v_mul_f32_e32 v27, 0x45800000, v26
	v_cndmask_b32_e32 v26, v26, v27, vcc
	v_mul_f32_e32 v18, v18, v26
	v_fma_f32 v8, v12, v18, v8
	v_mul_f32_e32 v12, 0xbfb8aa3b, v8
	v_exp_f32_e32 v12, v12
	s_nop 0
	v_add_f32_e32 v12, 1.0, v12
	v_rcp_f32_e32 v12, v12
	s_nop 0
	v_mul_f32_e32 v8, v8, v12
	v_mul_f32_e32 v12, v19, v26
	v_fma_f32 v9, v13, v12, v9
	v_mul_f32_e32 v12, 0xbfb8aa3b, v9
	v_exp_f32_e32 v12, v12
	s_nop 0
	v_add_f32_e32 v12, 1.0, v12
	v_rcp_f32_e32 v12, v12
	s_nop 0
	v_mul_f32_e32 v9, v9, v12
	v_mul_f32_e32 v12, v20, v26
	v_fma_f32 v10, v14, v12, v10
	v_mul_f32_e32 v12, 0xbfb8aa3b, v10
	v_exp_f32_e32 v12, v12
	s_nop 0
	v_add_f32_e32 v12, 1.0, v12
	v_rcp_f32_e32 v12, v12
	s_nop 0
	v_mul_f32_e32 v10, v10, v12
	v_mul_f32_e32 v12, v21, v26
	v_fmac_f32_e32 v11, v15, v12
	v_mul_f32_e32 v12, 0xbfb8aa3b, v11
	v_exp_f32_e32 v12, v12
	s_nop 0
	v_add_f32_e32 v12, 1.0, v12
	v_rcp_f32_e32 v12, v12
	s_nop 0
	v_mul_f32_e32 v11, v11, v12
	v_mul_f32_e32 v12, v22, v26
	v_fma_f32 v0, v4, v12, v0
	v_mul_f32_e32 v4, 0xbfb8aa3b, v0
	v_exp_f32_e32 v4, v4
	s_nop 0
	v_add_f32_e32 v4, 1.0, v4
	v_rcp_f32_e32 v4, v4
	s_nop 0
	v_mul_f32_e32 v4, v0, v4
	v_mul_f32_e32 v0, v23, v26
	v_fma_f32 v0, v5, v0, v1
	v_mul_f32_e32 v1, 0xbfb8aa3b, v0
	v_exp_f32_e32 v1, v1
	s_nop 0
	v_add_f32_e32 v1, 1.0, v1
	v_rcp_f32_e32 v1, v1
	s_nop 0
	v_mul_f32_e32 v5, v0, v1
	v_mul_f32_e32 v0, v24, v26
	v_fma_f32 v0, v6, v0, v2
	v_mul_f32_e32 v1, 0xbfb8aa3b, v0
	v_exp_f32_e32 v1, v1
	s_nop 0
	v_add_f32_e32 v1, 1.0, v1
	v_rcp_f32_e32 v1, v1
	s_nop 0
	v_mul_f32_e32 v6, v0, v1
	v_mul_f32_e32 v0, v25, v26
	v_fmac_f32_e32 v3, v7, v0
	v_mul_f32_e32 v0, 0xbfb8aa3b, v3
	v_exp_f32_e32 v0, v0
	s_nop 0
	v_add_f32_e32 v0, 1.0, v0
	v_rcp_f32_e32 v0, v0
	s_nop 0
	v_mul_f32_e32 v3, v3, v0
	v_cvt_pk_bf16_f32 v0, v8, v9
	v_cvt_pk_bf16_f32 v1, v10, v11
	v_cvt_pk_bf16_f32 v2, v4, v5
	v_lshlrev_b32_e32 v4, 10, v81
	v_ashrrev_i32_e32 v5, 31, v4
	v_lshl_add_u64 v[4:5], v[4:5], 1, v[16:17]
	v_cvt_pk_bf16_f32 v3, v6, v3
	global_store_dwordx4 v[4:5], v[0:3], off
	s_waitcnt lgkmcnt(0)
